# GEMM K-loops: per 16-MFMA group, accumulator pairs (k0,k1) back to back in serpentine (m,n) order so consecutive MFMAs share the accumulator or one source fragment; accumulation order unchanged
# speedup vs baseline: 1.0253x; 1.0070x over previous
.LBB0_131:
	ds_read_b128 v[146:149], v157
	ds_read_b128 v[150:153], v157 offset:1024
	ds_read_b128 v[160:163], v157 offset:2048
	ds_read_b128 v[164:167], v157 offset:3072
	ds_read_b128 v[168:171], v158
	ds_read_b128 v[172:175], v158 offset:1024
	ds_read_b128 v[176:179], v158 offset:2048
	ds_read_b128 v[180:183], v158 offset:3072
	s_add_u32 s34, s30, 0xfff80080
	s_addc_u32 s35, s31, -1
	s_cmp_eq_u32 s55, 28
	s_cselect_b32 s37, s23, s35
	s_cselect_b32 s36, s51, s34
	s_cselect_b32 s35, s21, s54
	s_cselect_b32 s34, s52, s53
	v_lshl_add_u64 v[216:217], s[30:31], 0, v[138:139]
	s_add_i32 m0, s29, 0xc000
	ds_read_b128 v[184:187], v159
	ds_read_b128 v[188:191], v159 offset:1024
	ds_read_b128 v[192:195], v159 offset:2048
	ds_read_b128 v[196:199], v159 offset:3072
	ds_read_b128 v[200:203], v159 offset:4096
	ds_read_b128 v[204:207], v159 offset:5120
	ds_read_b128 v[208:211], v159 offset:6144
	ds_read_b128 v[212:215], v159 offset:7168
	global_load_lds_dwordx4 v[216:217], off
	v_lshl_add_u64 v[216:217], s[30:31], 0, v[140:141]
	s_add_i32 m0, s29, 0xe000
	s_nop 0
	global_load_lds_dwordx4 v[216:217], off
	s_waitcnt vmcnt(8)
	s_waitcnt lgkmcnt(0)
	s_barrier
	s_setprio 1
	s_waitcnt lgkmcnt(0)
	v_mfma_f32_16x16x32_bf16 v[124:127], v[146:149], v[184:187], v[124:127]
	v_mfma_f32_16x16x32_bf16 v[124:127], v[150:153], v[188:191], v[124:127]
	v_mfma_f32_16x16x32_bf16 v[120:123], v[160:163], v[184:187], v[120:123]
	v_mfma_f32_16x16x32_bf16 v[120:123], v[164:167], v[188:191], v[120:123]
	v_mfma_f32_16x16x32_bf16 v[104:107], v[160:163], v[192:195], v[104:107]
	v_mfma_f32_16x16x32_bf16 v[104:107], v[164:167], v[196:199], v[104:107]
	v_mfma_f32_16x16x32_bf16 v[108:111], v[146:149], v[192:195], v[108:111]
	v_mfma_f32_16x16x32_bf16 v[108:111], v[150:153], v[196:199], v[108:111]
	v_mfma_f32_16x16x32_bf16 v[92:95], v[146:149], v[200:203], v[92:95]
	v_mfma_f32_16x16x32_bf16 v[92:95], v[150:153], v[204:207], v[92:95]
	v_mfma_f32_16x16x32_bf16 v[88:91], v[160:163], v[200:203], v[88:91]
	v_mfma_f32_16x16x32_bf16 v[88:91], v[164:167], v[204:207], v[88:91]
	v_mfma_f32_16x16x32_bf16 v[72:75], v[160:163], v[208:211], v[72:75]
	v_mfma_f32_16x16x32_bf16 v[72:75], v[164:167], v[212:215], v[72:75]
	v_mfma_f32_16x16x32_bf16 v[76:79], v[146:149], v[208:211], v[76:79]
	v_mfma_f32_16x16x32_bf16 v[76:79], v[150:153], v[212:215], v[76:79]
	s_setprio 0
	s_setprio 1
	v_mfma_f32_16x16x32_bf16 v[116:119], v[168:171], v[184:187], v[116:119]
	v_mfma_f32_16x16x32_bf16 v[116:119], v[172:175], v[188:191], v[116:119]
	v_mfma_f32_16x16x32_bf16 v[112:115], v[176:179], v[184:187], v[112:115]
	v_mfma_f32_16x16x32_bf16 v[112:115], v[180:183], v[188:191], v[112:115]
	v_mfma_f32_16x16x32_bf16 v[96:99], v[176:179], v[192:195], v[96:99]
	v_mfma_f32_16x16x32_bf16 v[96:99], v[180:183], v[196:199], v[96:99]
	v_mfma_f32_16x16x32_bf16 v[100:103], v[168:171], v[192:195], v[100:103]
	v_mfma_f32_16x16x32_bf16 v[100:103], v[172:175], v[196:199], v[100:103]
	v_mfma_f32_16x16x32_bf16 v[84:87], v[168:171], v[200:203], v[84:87]
	v_mfma_f32_16x16x32_bf16 v[84:87], v[172:175], v[204:207], v[84:87]
	v_mfma_f32_16x16x32_bf16 v[80:83], v[176:179], v[200:203], v[80:83]
	v_mfma_f32_16x16x32_bf16 v[80:83], v[180:183], v[204:207], v[80:83]
	v_mfma_f32_16x16x32_bf16 v[64:67], v[176:179], v[208:211], v[64:67]
	v_mfma_f32_16x16x32_bf16 v[64:67], v[180:183], v[212:215], v[64:67]
	v_mfma_f32_16x16x32_bf16 v[68:71], v[168:171], v[208:211], v[68:71]
	v_mfma_f32_16x16x32_bf16 v[68:71], v[172:175], v[212:215], v[68:71]
	s_setprio 0
	s_barrier
	s_add_i32 s56, s47, s33
	v_lshl_add_u64 v[216:217], s[34:35], 0, v[134:135]
	s_mov_b32 m0, s56
	ds_read_b128 v[184:187], v159 offset:16384
	ds_read_b128 v[188:191], v159 offset:17408
	ds_read_b128 v[192:195], v159 offset:18432
	ds_read_b128 v[196:199], v159 offset:19456
	ds_read_b128 v[200:203], v159 offset:20480
	ds_read_b128 v[204:207], v159 offset:21504
	ds_read_b128 v[208:211], v159 offset:22528
	ds_read_b128 v[212:215], v159 offset:23552
	global_load_lds_dwordx4 v[216:217], off
	s_add_i32 m0, s56, 0x2000
	s_add_u32 s56, s34, 0x80000
	v_lshl_add_u64 v[218:219], s[34:35], 0, v[130:131]
	s_addc_u32 s57, s35, 0
	s_add_i32 s58, s48, s33
	global_load_lds_dwordx4 v[218:219], off
	v_lshl_add_u64 v[220:221], s[56:57], 0, v[134:135]
	s_mov_b32 m0, s58
	v_lshl_add_u64 v[222:223], s[36:37], 0, v[132:133]
	global_load_lds_dwordx4 v[220:221], off
	v_lshl_add_u64 v[220:221], s[56:57], 0, v[130:131]
	s_add_i32 m0, s58, 0x2000
	s_nop 0
	global_load_lds_dwordx4 v[220:221], off
	v_lshl_add_u64 v[220:221], s[36:37], 0, v[136:137]
	s_mov_b32 m0, s29
	s_nop 0
	global_load_lds_dwordx4 v[220:221], off
	s_mov_b32 m0, s40
	s_nop 0
	global_load_lds_dwordx4 v[222:223], off
	s_waitcnt vmcnt(8)
	s_waitcnt lgkmcnt(0)
	s_barrier
	s_setprio 1
	s_waitcnt lgkmcnt(0)
	v_mfma_f32_16x16x32_bf16 v[60:63], v[146:149], v[184:187], v[60:63]
	v_mfma_f32_16x16x32_bf16 v[60:63], v[150:153], v[188:191], v[60:63]
	v_mfma_f32_16x16x32_bf16 v[56:59], v[160:163], v[184:187], v[56:59]
	v_mfma_f32_16x16x32_bf16 v[56:59], v[164:167], v[188:191], v[56:59]
	v_mfma_f32_16x16x32_bf16 v[40:43], v[160:163], v[192:195], v[40:43]
	v_mfma_f32_16x16x32_bf16 v[40:43], v[164:167], v[196:199], v[40:43]
	v_mfma_f32_16x16x32_bf16 v[44:47], v[146:149], v[192:195], v[44:47]
	v_mfma_f32_16x16x32_bf16 v[44:47], v[150:153], v[196:199], v[44:47]
	v_mfma_f32_16x16x32_bf16 v[28:31], v[146:149], v[200:203], v[28:31]
	v_mfma_f32_16x16x32_bf16 v[28:31], v[150:153], v[204:207], v[28:31]
	v_mfma_f32_16x16x32_bf16 v[24:27], v[160:163], v[200:203], v[24:27]
	v_mfma_f32_16x16x32_bf16 v[24:27], v[164:167], v[204:207], v[24:27]
	v_mfma_f32_16x16x32_bf16 v[8:11], v[160:163], v[208:211], v[8:11]
	v_mfma_f32_16x16x32_bf16 v[8:11], v[164:167], v[212:215], v[8:11]
	v_mfma_f32_16x16x32_bf16 v[12:15], v[146:149], v[208:211], v[12:15]
	v_mfma_f32_16x16x32_bf16 v[12:15], v[150:153], v[212:215], v[12:15]
	s_setprio 0
	s_setprio 1
	v_mfma_f32_16x16x32_bf16 v[52:55], v[168:171], v[184:187], v[52:55]
	v_mfma_f32_16x16x32_bf16 v[52:55], v[172:175], v[188:191], v[52:55]
	v_mfma_f32_16x16x32_bf16 v[48:51], v[176:179], v[184:187], v[48:51]
	v_mfma_f32_16x16x32_bf16 v[48:51], v[180:183], v[188:191], v[48:51]
	v_mfma_f32_16x16x32_bf16 v[32:35], v[176:179], v[192:195], v[32:35]
	v_mfma_f32_16x16x32_bf16 v[32:35], v[180:183], v[196:199], v[32:35]
	v_mfma_f32_16x16x32_bf16 v[36:39], v[168:171], v[192:195], v[36:39]
	v_mfma_f32_16x16x32_bf16 v[36:39], v[172:175], v[196:199], v[36:39]
	v_mfma_f32_16x16x32_bf16 v[20:23], v[168:171], v[200:203], v[20:23]
	v_mfma_f32_16x16x32_bf16 v[20:23], v[172:175], v[204:207], v[20:23]
	v_mfma_f32_16x16x32_bf16 v[16:19], v[176:179], v[200:203], v[16:19]
	v_mfma_f32_16x16x32_bf16 v[16:19], v[180:183], v[204:207], v[16:19]
	v_mfma_f32_16x16x32_bf16 v[0:3], v[176:179], v[208:211], v[0:3]
	v_mfma_f32_16x16x32_bf16 v[0:3], v[180:183], v[212:215], v[0:3]
	v_mfma_f32_16x16x32_bf16 v[4:7], v[168:171], v[208:211], v[4:7]
	v_mfma_f32_16x16x32_bf16 v[4:7], v[172:175], v[212:215], v[4:7]
	s_setprio 0
	s_barrier
	s_add_i32 s56, 0, 0x18000
	s_add_i32 s57, 0, 0x1c000
	v_add_u32_e32 v164, s56, v155
	v_add_u32_e32 v180, s57, v155
	ds_read_b128 v[146:149], v164
	ds_read_b128 v[150:153], v164 offset:1024
	ds_read_b128 v[160:163], v164 offset:2048
	ds_read_b128 v[164:167], v164 offset:3072
	ds_read_b128 v[168:171], v180
	ds_read_b128 v[172:175], v180 offset:1024
	ds_read_b128 v[176:179], v180 offset:2048
	ds_read_b128 v[180:183], v180 offset:3072
	s_add_u32 s36, s36, 0x80000
	s_addc_u32 s37, s37, 0
	s_mov_b32 m0, s41
	v_lshl_add_u64 v[224:225], s[36:37], 0, v[136:137]
	ds_read_b128 v[184:187], v159 offset:32768
	ds_read_b128 v[188:191], v159 offset:33792
	ds_read_b128 v[192:195], v159 offset:34816
	ds_read_b128 v[196:199], v159 offset:35840
	ds_read_b128 v[200:203], v159 offset:36864
	ds_read_b128 v[204:207], v159 offset:37888
	ds_read_b128 v[208:211], v159 offset:38912
	ds_read_b128 v[212:215], v159 offset:39936
	global_load_lds_dwordx4 v[224:225], off
	v_lshl_add_u64 v[224:225], s[36:37], 0, v[132:133]
	s_mov_b32 m0, s42
	s_nop 0
	global_load_lds_dwordx4 v[224:225], off
	s_waitcnt vmcnt(8)
	s_waitcnt lgkmcnt(0)
	s_barrier
	s_setprio 1
	s_waitcnt lgkmcnt(0)
	v_mfma_f32_16x16x32_bf16 v[124:127], v[146:149], v[184:187], v[124:127]
	v_mfma_f32_16x16x32_bf16 v[124:127], v[150:153], v[188:191], v[124:127]
	v_mfma_f32_16x16x32_bf16 v[120:123], v[160:163], v[184:187], v[120:123]
	v_mfma_f32_16x16x32_bf16 v[120:123], v[164:167], v[188:191], v[120:123]
	v_mfma_f32_16x16x32_bf16 v[104:107], v[160:163], v[192:195], v[104:107]
	v_mfma_f32_16x16x32_bf16 v[104:107], v[164:167], v[196:199], v[104:107]
	v_mfma_f32_16x16x32_bf16 v[108:111], v[146:149], v[192:195], v[108:111]
	v_mfma_f32_16x16x32_bf16 v[108:111], v[150:153], v[196:199], v[108:111]
	v_mfma_f32_16x16x32_bf16 v[92:95], v[146:149], v[200:203], v[92:95]
	v_mfma_f32_16x16x32_bf16 v[92:95], v[150:153], v[204:207], v[92:95]
	v_mfma_f32_16x16x32_bf16 v[88:91], v[160:163], v[200:203], v[88:91]
	v_mfma_f32_16x16x32_bf16 v[88:91], v[164:167], v[204:207], v[88:91]
	v_mfma_f32_16x16x32_bf16 v[72:75], v[160:163], v[208:211], v[72:75]
	v_mfma_f32_16x16x32_bf16 v[72:75], v[164:167], v[212:215], v[72:75]
	v_mfma_f32_16x16x32_bf16 v[76:79], v[146:149], v[208:211], v[76:79]
	v_mfma_f32_16x16x32_bf16 v[76:79], v[150:153], v[212:215], v[76:79]
	s_setprio 0
	s_setprio 1
	v_mfma_f32_16x16x32_bf16 v[116:119], v[168:171], v[184:187], v[116:119]
	v_mfma_f32_16x16x32_bf16 v[116:119], v[172:175], v[188:191], v[116:119]
	v_mfma_f32_16x16x32_bf16 v[112:115], v[176:179], v[184:187], v[112:115]
	v_mfma_f32_16x16x32_bf16 v[112:115], v[180:183], v[188:191], v[112:115]
	v_mfma_f32_16x16x32_bf16 v[96:99], v[176:179], v[192:195], v[96:99]
	v_mfma_f32_16x16x32_bf16 v[96:99], v[180:183], v[196:199], v[96:99]
	v_mfma_f32_16x16x32_bf16 v[100:103], v[168:171], v[192:195], v[100:103]
	v_mfma_f32_16x16x32_bf16 v[100:103], v[172:175], v[196:199], v[100:103]
	v_mfma_f32_16x16x32_bf16 v[84:87], v[168:171], v[200:203], v[84:87]
	v_mfma_f32_16x16x32_bf16 v[84:87], v[172:175], v[204:207], v[84:87]
	v_mfma_f32_16x16x32_bf16 v[80:83], v[176:179], v[200:203], v[80:83]
	v_mfma_f32_16x16x32_bf16 v[80:83], v[180:183], v[204:207], v[80:83]
	v_mfma_f32_16x16x32_bf16 v[64:67], v[176:179], v[208:211], v[64:67]
	v_mfma_f32_16x16x32_bf16 v[64:67], v[180:183], v[212:215], v[64:67]
	v_mfma_f32_16x16x32_bf16 v[68:71], v[168:171], v[208:211], v[68:71]
	v_mfma_f32_16x16x32_bf16 v[68:71], v[172:175], v[212:215], v[68:71]
	s_setprio 0
	s_barrier
	s_add_i32 s36, s56, s33
	v_lshl_add_u64 v[216:217], v[216:217], 0, s[14:15]
	s_mov_b32 m0, s36
	ds_read_b128 v[184:187], v159 offset:49152
	ds_read_b128 v[188:191], v159 offset:50176
	ds_read_b128 v[192:195], v159 offset:51200
	ds_read_b128 v[196:199], v159 offset:52224
	ds_read_b128 v[200:203], v159 offset:53248
	ds_read_b128 v[204:207], v159 offset:54272
	ds_read_b128 v[208:211], v159 offset:55296
	ds_read_b128 v[212:215], v159 offset:56320
	global_load_lds_dwordx4 v[216:217], off
	s_add_i32 m0, s36, 0x2000
	s_add_u32 s34, s34, 0x80080
	v_lshl_add_u64 v[216:217], v[218:219], 0, s[14:15]
	s_addc_u32 s35, s35, 0
	s_add_i32 s36, s57, s33
	global_load_lds_dwordx4 v[216:217], off
	v_lshl_add_u64 v[216:217], s[34:35], 0, v[134:135]
	s_mov_b32 m0, s36
	s_nop 0
	global_load_lds_dwordx4 v[216:217], off
	v_lshl_add_u64 v[216:217], s[34:35], 0, v[130:131]
	s_add_i32 m0, s36, 0x2000
	s_nop 0
	global_load_lds_dwordx4 v[216:217], off
	v_lshl_add_u64 v[216:217], v[220:221], 0, s[14:15]
	s_mov_b32 m0, s44
	s_nop 0
	global_load_lds_dwordx4 v[216:217], off
	v_lshl_add_u64 v[216:217], v[222:223], 0, s[14:15]
	s_mov_b32 m0, s45
	s_nop 0
	global_load_lds_dwordx4 v[216:217], off
	s_waitcnt vmcnt(8)
	s_waitcnt lgkmcnt(0)
	s_barrier
	s_setprio 1
	s_waitcnt lgkmcnt(0)
	v_mfma_f32_16x16x32_bf16 v[60:63], v[146:149], v[184:187], v[60:63]
	v_mfma_f32_16x16x32_bf16 v[60:63], v[150:153], v[188:191], v[60:63]
	v_mfma_f32_16x16x32_bf16 v[56:59], v[160:163], v[184:187], v[56:59]
	v_mfma_f32_16x16x32_bf16 v[56:59], v[164:167], v[188:191], v[56:59]
	v_mfma_f32_16x16x32_bf16 v[40:43], v[160:163], v[192:195], v[40:43]
	v_mfma_f32_16x16x32_bf16 v[40:43], v[164:167], v[196:199], v[40:43]
	v_mfma_f32_16x16x32_bf16 v[44:47], v[146:149], v[192:195], v[44:47]
	v_mfma_f32_16x16x32_bf16 v[44:47], v[150:153], v[196:199], v[44:47]
	v_mfma_f32_16x16x32_bf16 v[28:31], v[146:149], v[200:203], v[28:31]
	v_mfma_f32_16x16x32_bf16 v[28:31], v[150:153], v[204:207], v[28:31]
	v_mfma_f32_16x16x32_bf16 v[24:27], v[160:163], v[200:203], v[24:27]
	v_mfma_f32_16x16x32_bf16 v[24:27], v[164:167], v[204:207], v[24:27]
	v_mfma_f32_16x16x32_bf16 v[8:11], v[160:163], v[208:211], v[8:11]
	v_mfma_f32_16x16x32_bf16 v[8:11], v[164:167], v[212:215], v[8:11]
	v_mfma_f32_16x16x32_bf16 v[12:15], v[146:149], v[208:211], v[12:15]
	v_mfma_f32_16x16x32_bf16 v[12:15], v[150:153], v[212:215], v[12:15]
	s_setprio 0
	s_setprio 1
	v_mfma_f32_16x16x32_bf16 v[52:55], v[168:171], v[184:187], v[52:55]
	v_mfma_f32_16x16x32_bf16 v[52:55], v[172:175], v[188:191], v[52:55]
	v_mfma_f32_16x16x32_bf16 v[48:51], v[176:179], v[184:187], v[48:51]
	v_mfma_f32_16x16x32_bf16 v[48:51], v[180:183], v[188:191], v[48:51]
	v_mfma_f32_16x16x32_bf16 v[32:35], v[176:179], v[192:195], v[32:35]
	v_mfma_f32_16x16x32_bf16 v[32:35], v[180:183], v[196:199], v[32:35]
	v_mfma_f32_16x16x32_bf16 v[36:39], v[168:171], v[192:195], v[36:39]
	v_mfma_f32_16x16x32_bf16 v[36:39], v[172:175], v[196:199], v[36:39]
	v_mfma_f32_16x16x32_bf16 v[20:23], v[168:171], v[200:203], v[20:23]
	v_mfma_f32_16x16x32_bf16 v[20:23], v[172:175], v[204:207], v[20:23]
	v_mfma_f32_16x16x32_bf16 v[16:19], v[176:179], v[200:203], v[16:19]
	v_mfma_f32_16x16x32_bf16 v[16:19], v[180:183], v[204:207], v[16:19]
	v_mfma_f32_16x16x32_bf16 v[0:3], v[176:179], v[208:211], v[0:3]
	v_mfma_f32_16x16x32_bf16 v[0:3], v[180:183], v[212:215], v[0:3]
	v_mfma_f32_16x16x32_bf16 v[4:7], v[168:171], v[208:211], v[4:7]
	v_mfma_f32_16x16x32_bf16 v[4:7], v[172:175], v[212:215], v[4:7]
	s_setprio 0
	s_barrier
	s_add_i32 s55, s55, 2
	s_add_u32 s30, s30, 0x100
	s_addc_u32 s31, s31, 0
	s_add_u32 s53, s53, 0x100
	s_addc_u32 s54, s54, 0
	s_cmp_gt_u32 s55, 29
	s_cbranch_scc0 .LBB0_131
	s_and_b64 vcc, exec, s[18:19]
	s_cbranch_vccz .LBB0_134
	s_barrier

.LBB0_585:
	v_add_u32_e32 v166, s42, v152
	v_add_u32_e32 v182, s43, v152
	s_add_u32 s26, s12, s24
	ds_read_b128 v[154:157], v166
	ds_read_b128 v[158:161], v166 offset:1024
	ds_read_b128 v[162:165], v166 offset:2048
	ds_read_b128 v[166:169], v166 offset:3072
	ds_read_b128 v[170:173], v182
	ds_read_b128 v[174:177], v182 offset:1024
	ds_read_b128 v[178:181], v182 offset:2048
	ds_read_b128 v[182:185], v182 offset:3072
	s_addc_u32 s27, s13, s25
	s_add_u32 s26, s26, 0x100
	s_addc_u32 s27, s27, 0
	s_add_u32 s50, s45, s24
	s_addc_u32 s51, s46, s25
	s_cmpk_eq_i32 s24, 0xf00
	s_cselect_b32 s29, s19, s27
	s_cselect_b32 s28, s47, s26
	s_cselect_b32 s27, s17, s51
	s_cselect_b32 s26, s48, s50
	v_lshl_add_u64 v[218:219], v[146:147], 0, s[24:25]
	s_add_i32 m0, s11, 0xc000
	ds_read_b128 v[186:189], v153
	ds_read_b128 v[190:193], v153 offset:1024
	ds_read_b128 v[194:197], v153 offset:2048
	ds_read_b128 v[198:201], v153 offset:3072
	ds_read_b128 v[202:205], v153 offset:4096
	ds_read_b128 v[206:209], v153 offset:5120
	ds_read_b128 v[210:213], v153 offset:6144
	ds_read_b128 v[214:217], v153 offset:7168
	global_load_lds_dwordx4 v[218:219], off
	v_lshl_add_u64 v[218:219], v[148:149], 0, s[24:25]
	s_add_i32 m0, s11, 0xe000
	s_nop 0
	global_load_lds_dwordx4 v[218:219], off
	s_waitcnt vmcnt(8)
	s_waitcnt lgkmcnt(0)
	s_barrier
	s_setprio 1
	s_waitcnt lgkmcnt(0)
	v_mfma_f32_16x16x32_bf16 v[124:127], v[154:157], v[186:189], v[124:127]
	v_mfma_f32_16x16x32_bf16 v[124:127], v[158:161], v[190:193], v[124:127]
	v_mfma_f32_16x16x32_bf16 v[120:123], v[162:165], v[186:189], v[120:123]
	v_mfma_f32_16x16x32_bf16 v[120:123], v[166:169], v[190:193], v[120:123]
	v_mfma_f32_16x16x32_bf16 v[104:107], v[162:165], v[194:197], v[104:107]
	v_mfma_f32_16x16x32_bf16 v[104:107], v[166:169], v[198:201], v[104:107]
	v_mfma_f32_16x16x32_bf16 v[108:111], v[154:157], v[194:197], v[108:111]
	v_mfma_f32_16x16x32_bf16 v[108:111], v[158:161], v[198:201], v[108:111]
	v_mfma_f32_16x16x32_bf16 v[92:95], v[154:157], v[202:205], v[92:95]
	v_mfma_f32_16x16x32_bf16 v[92:95], v[158:161], v[206:209], v[92:95]
	v_mfma_f32_16x16x32_bf16 v[88:91], v[162:165], v[202:205], v[88:91]
	v_mfma_f32_16x16x32_bf16 v[88:91], v[166:169], v[206:209], v[88:91]
	v_mfma_f32_16x16x32_bf16 v[72:75], v[162:165], v[210:213], v[72:75]
	v_mfma_f32_16x16x32_bf16 v[72:75], v[166:169], v[214:217], v[72:75]
	v_mfma_f32_16x16x32_bf16 v[76:79], v[154:157], v[210:213], v[76:79]
	v_mfma_f32_16x16x32_bf16 v[76:79], v[158:161], v[214:217], v[76:79]
	s_setprio 0
	s_setprio 1
	v_mfma_f32_16x16x32_bf16 v[116:119], v[170:173], v[186:189], v[116:119]
	v_mfma_f32_16x16x32_bf16 v[116:119], v[174:177], v[190:193], v[116:119]
	v_mfma_f32_16x16x32_bf16 v[112:115], v[178:181], v[186:189], v[112:115]
	v_mfma_f32_16x16x32_bf16 v[112:115], v[182:185], v[190:193], v[112:115]
	v_mfma_f32_16x16x32_bf16 v[96:99], v[178:181], v[194:197], v[96:99]
	v_mfma_f32_16x16x32_bf16 v[96:99], v[182:185], v[198:201], v[96:99]
	v_mfma_f32_16x16x32_bf16 v[100:103], v[170:173], v[194:197], v[100:103]
	v_mfma_f32_16x16x32_bf16 v[100:103], v[174:177], v[198:201], v[100:103]
	v_mfma_f32_16x16x32_bf16 v[84:87], v[170:173], v[202:205], v[84:87]
	v_mfma_f32_16x16x32_bf16 v[84:87], v[174:177], v[206:209], v[84:87]
	v_mfma_f32_16x16x32_bf16 v[80:83], v[178:181], v[202:205], v[80:83]
	v_mfma_f32_16x16x32_bf16 v[80:83], v[182:185], v[206:209], v[80:83]
	v_mfma_f32_16x16x32_bf16 v[64:67], v[178:181], v[210:213], v[64:67]
	v_mfma_f32_16x16x32_bf16 v[64:67], v[182:185], v[214:217], v[64:67]
	v_mfma_f32_16x16x32_bf16 v[68:71], v[170:173], v[210:213], v[68:71]
	v_mfma_f32_16x16x32_bf16 v[68:71], v[174:177], v[214:217], v[68:71]
	s_setprio 0
	s_barrier
	s_add_i32 s50, s42, s35
	v_lshl_add_u64 v[218:219], s[26:27], 0, v[132:133]
	s_mov_b32 m0, s50
	ds_read_b128 v[186:189], v153 offset:16384
	ds_read_b128 v[190:193], v153 offset:17408
	ds_read_b128 v[194:197], v153 offset:18432
	ds_read_b128 v[198:201], v153 offset:19456
	ds_read_b128 v[202:205], v153 offset:20480
	ds_read_b128 v[206:209], v153 offset:21504
	ds_read_b128 v[210:213], v153 offset:22528
	ds_read_b128 v[214:217], v153 offset:23552
	global_load_lds_dwordx4 v[218:219], off
	s_add_i32 m0, s50, 0x2000
	s_add_u32 s50, s26, 0x80000
	v_lshl_add_u64 v[220:221], s[26:27], 0, v[136:137]
	s_addc_u32 s51, s27, 0
	s_add_i32 s52, s43, s35
	global_load_lds_dwordx4 v[220:221], off
	v_lshl_add_u64 v[222:223], s[50:51], 0, v[132:133]
	s_mov_b32 m0, s52
	v_lshl_add_u64 v[224:225], s[28:29], 0, v[134:135]
	global_load_lds_dwordx4 v[222:223], off
	v_lshl_add_u64 v[222:223], s[50:51], 0, v[136:137]
	s_add_i32 m0, s52, 0x2000
	s_nop 0
	global_load_lds_dwordx4 v[222:223], off
	v_lshl_add_u64 v[222:223], s[28:29], 0, v[130:131]
	s_mov_b32 m0, s11
	s_nop 0
	global_load_lds_dwordx4 v[222:223], off
	s_mov_b32 m0, s36
	s_nop 0
	global_load_lds_dwordx4 v[224:225], off
	s_waitcnt vmcnt(8)
	s_waitcnt lgkmcnt(0)
	s_barrier
	s_setprio 1
	s_waitcnt lgkmcnt(0)
	v_mfma_f32_16x16x32_bf16 v[60:63], v[154:157], v[186:189], v[60:63]
	v_mfma_f32_16x16x32_bf16 v[60:63], v[158:161], v[190:193], v[60:63]
	v_mfma_f32_16x16x32_bf16 v[56:59], v[162:165], v[186:189], v[56:59]
	v_mfma_f32_16x16x32_bf16 v[56:59], v[166:169], v[190:193], v[56:59]
	v_mfma_f32_16x16x32_bf16 v[40:43], v[162:165], v[194:197], v[40:43]
	v_mfma_f32_16x16x32_bf16 v[40:43], v[166:169], v[198:201], v[40:43]
	v_mfma_f32_16x16x32_bf16 v[44:47], v[154:157], v[194:197], v[44:47]
	v_mfma_f32_16x16x32_bf16 v[44:47], v[158:161], v[198:201], v[44:47]
	v_mfma_f32_16x16x32_bf16 v[28:31], v[154:157], v[202:205], v[28:31]
	v_mfma_f32_16x16x32_bf16 v[28:31], v[158:161], v[206:209], v[28:31]
	v_mfma_f32_16x16x32_bf16 v[24:27], v[162:165], v[202:205], v[24:27]
	v_mfma_f32_16x16x32_bf16 v[24:27], v[166:169], v[206:209], v[24:27]
	v_mfma_f32_16x16x32_bf16 v[8:11], v[162:165], v[210:213], v[8:11]
	v_mfma_f32_16x16x32_bf16 v[8:11], v[166:169], v[214:217], v[8:11]
	v_mfma_f32_16x16x32_bf16 v[12:15], v[154:157], v[210:213], v[12:15]
	v_mfma_f32_16x16x32_bf16 v[12:15], v[158:161], v[214:217], v[12:15]
	s_setprio 0
	s_setprio 1
	v_mfma_f32_16x16x32_bf16 v[52:55], v[170:173], v[186:189], v[52:55]
	v_mfma_f32_16x16x32_bf16 v[52:55], v[174:177], v[190:193], v[52:55]
	v_mfma_f32_16x16x32_bf16 v[48:51], v[178:181], v[186:189], v[48:51]
	v_mfma_f32_16x16x32_bf16 v[48:51], v[182:185], v[190:193], v[48:51]
	v_mfma_f32_16x16x32_bf16 v[32:35], v[178:181], v[194:197], v[32:35]
	v_mfma_f32_16x16x32_bf16 v[32:35], v[182:185], v[198:201], v[32:35]
	v_mfma_f32_16x16x32_bf16 v[36:39], v[170:173], v[194:197], v[36:39]
	v_mfma_f32_16x16x32_bf16 v[36:39], v[174:177], v[198:201], v[36:39]
	v_mfma_f32_16x16x32_bf16 v[20:23], v[170:173], v[202:205], v[20:23]
	v_mfma_f32_16x16x32_bf16 v[20:23], v[174:177], v[206:209], v[20:23]
	v_mfma_f32_16x16x32_bf16 v[16:19], v[178:181], v[202:205], v[16:19]
	v_mfma_f32_16x16x32_bf16 v[16:19], v[182:185], v[206:209], v[16:19]
	v_mfma_f32_16x16x32_bf16 v[0:3], v[178:181], v[210:213], v[0:3]
	v_mfma_f32_16x16x32_bf16 v[0:3], v[182:185], v[214:217], v[0:3]
	v_mfma_f32_16x16x32_bf16 v[4:7], v[170:173], v[210:213], v[4:7]
	v_mfma_f32_16x16x32_bf16 v[4:7], v[174:177], v[214:217], v[4:7]
	s_setprio 0
	s_barrier
	s_add_i32 s50, 0, 0x18000
	s_add_i32 s51, 0, 0x1c000
	v_add_u32_e32 v166, s50, v152
	v_add_u32_e32 v182, s51, v152
	ds_read_b128 v[154:157], v166
	ds_read_b128 v[158:161], v166 offset:1024
	ds_read_b128 v[162:165], v166 offset:2048
	ds_read_b128 v[166:169], v166 offset:3072
	ds_read_b128 v[170:173], v182
	ds_read_b128 v[174:177], v182 offset:1024
	ds_read_b128 v[178:181], v182 offset:2048
	ds_read_b128 v[182:185], v182 offset:3072
	s_add_u32 s28, s28, 0x80000
	s_addc_u32 s29, s29, 0
	s_mov_b32 m0, s37
	v_lshl_add_u64 v[226:227], s[28:29], 0, v[130:131]
	ds_read_b128 v[186:189], v153 offset:32768
	ds_read_b128 v[190:193], v153 offset:33792
	ds_read_b128 v[194:197], v153 offset:34816
	ds_read_b128 v[198:201], v153 offset:35840
	ds_read_b128 v[202:205], v153 offset:36864
	ds_read_b128 v[206:209], v153 offset:37888
	ds_read_b128 v[210:213], v153 offset:38912
	ds_read_b128 v[214:217], v153 offset:39936
	global_load_lds_dwordx4 v[226:227], off
	v_lshl_add_u64 v[226:227], s[28:29], 0, v[134:135]
	s_mov_b32 m0, s38
	s_nop 0
	global_load_lds_dwordx4 v[226:227], off
	s_waitcnt vmcnt(8)
	s_waitcnt lgkmcnt(0)
	s_barrier
	s_setprio 1
	s_waitcnt lgkmcnt(0)
	v_mfma_f32_16x16x32_bf16 v[124:127], v[154:157], v[186:189], v[124:127]
	v_mfma_f32_16x16x32_bf16 v[124:127], v[158:161], v[190:193], v[124:127]
	v_mfma_f32_16x16x32_bf16 v[120:123], v[162:165], v[186:189], v[120:123]
	v_mfma_f32_16x16x32_bf16 v[120:123], v[166:169], v[190:193], v[120:123]
	v_mfma_f32_16x16x32_bf16 v[104:107], v[162:165], v[194:197], v[104:107]
	v_mfma_f32_16x16x32_bf16 v[104:107], v[166:169], v[198:201], v[104:107]
	v_mfma_f32_16x16x32_bf16 v[108:111], v[154:157], v[194:197], v[108:111]
	v_mfma_f32_16x16x32_bf16 v[108:111], v[158:161], v[198:201], v[108:111]
	v_mfma_f32_16x16x32_bf16 v[92:95], v[154:157], v[202:205], v[92:95]
	v_mfma_f32_16x16x32_bf16 v[92:95], v[158:161], v[206:209], v[92:95]
	v_mfma_f32_16x16x32_bf16 v[88:91], v[162:165], v[202:205], v[88:91]
	v_mfma_f32_16x16x32_bf16 v[88:91], v[166:169], v[206:209], v[88:91]
	v_mfma_f32_16x16x32_bf16 v[72:75], v[162:165], v[210:213], v[72:75]
	v_mfma_f32_16x16x32_bf16 v[72:75], v[166:169], v[214:217], v[72:75]
	v_mfma_f32_16x16x32_bf16 v[76:79], v[154:157], v[210:213], v[76:79]
	v_mfma_f32_16x16x32_bf16 v[76:79], v[158:161], v[214:217], v[76:79]
	s_setprio 0
	s_setprio 1
	v_mfma_f32_16x16x32_bf16 v[116:119], v[170:173], v[186:189], v[116:119]
	v_mfma_f32_16x16x32_bf16 v[116:119], v[174:177], v[190:193], v[116:119]
	v_mfma_f32_16x16x32_bf16 v[112:115], v[178:181], v[186:189], v[112:115]
	v_mfma_f32_16x16x32_bf16 v[112:115], v[182:185], v[190:193], v[112:115]
	v_mfma_f32_16x16x32_bf16 v[96:99], v[178:181], v[194:197], v[96:99]
	v_mfma_f32_16x16x32_bf16 v[96:99], v[182:185], v[198:201], v[96:99]
	v_mfma_f32_16x16x32_bf16 v[100:103], v[170:173], v[194:197], v[100:103]
	v_mfma_f32_16x16x32_bf16 v[100:103], v[174:177], v[198:201], v[100:103]
	v_mfma_f32_16x16x32_bf16 v[84:87], v[170:173], v[202:205], v[84:87]
	v_mfma_f32_16x16x32_bf16 v[84:87], v[174:177], v[206:209], v[84:87]
	v_mfma_f32_16x16x32_bf16 v[80:83], v[178:181], v[202:205], v[80:83]
	v_mfma_f32_16x16x32_bf16 v[80:83], v[182:185], v[206:209], v[80:83]
	v_mfma_f32_16x16x32_bf16 v[64:67], v[178:181], v[210:213], v[64:67]
	v_mfma_f32_16x16x32_bf16 v[64:67], v[182:185], v[214:217], v[64:67]
	v_mfma_f32_16x16x32_bf16 v[68:71], v[170:173], v[210:213], v[68:71]
	v_mfma_f32_16x16x32_bf16 v[68:71], v[174:177], v[214:217], v[68:71]
	s_setprio 0
	s_barrier
	s_add_i32 s28, s50, s35
	v_lshl_add_u64 v[218:219], v[218:219], 0, s[14:15]
	s_mov_b32 m0, s28
	ds_read_b128 v[186:189], v153 offset:49152
	ds_read_b128 v[190:193], v153 offset:50176
	ds_read_b128 v[194:197], v153 offset:51200
	ds_read_b128 v[198:201], v153 offset:52224
	ds_read_b128 v[202:205], v153 offset:53248
	ds_read_b128 v[206:209], v153 offset:54272
	ds_read_b128 v[210:213], v153 offset:55296
	ds_read_b128 v[214:217], v153 offset:56320
	global_load_lds_dwordx4 v[218:219], off
	s_add_i32 m0, s28, 0x2000
	s_add_u32 s26, s26, 0x80080
	v_lshl_add_u64 v[218:219], v[220:221], 0, s[14:15]
	s_addc_u32 s27, s27, 0
	s_add_i32 s28, s51, s35
	global_load_lds_dwordx4 v[218:219], off
	v_lshl_add_u64 v[218:219], s[26:27], 0, v[132:133]
	s_mov_b32 m0, s28
	s_nop 0
	global_load_lds_dwordx4 v[218:219], off
	v_lshl_add_u64 v[218:219], s[26:27], 0, v[136:137]
	s_add_i32 m0, s28, 0x2000
	s_nop 0
	global_load_lds_dwordx4 v[218:219], off
	v_lshl_add_u64 v[218:219], v[222:223], 0, s[14:15]
	s_mov_b32 m0, s39
	s_nop 0
	global_load_lds_dwordx4 v[218:219], off
	v_lshl_add_u64 v[218:219], v[224:225], 0, s[14:15]
	s_mov_b32 m0, s40
	s_nop 0
	global_load_lds_dwordx4 v[218:219], off
	s_waitcnt vmcnt(8)
	s_waitcnt lgkmcnt(0)
	s_barrier
	s_setprio 1
	s_waitcnt lgkmcnt(0)
	v_mfma_f32_16x16x32_bf16 v[60:63], v[154:157], v[186:189], v[60:63]
	v_mfma_f32_16x16x32_bf16 v[60:63], v[158:161], v[190:193], v[60:63]
	v_mfma_f32_16x16x32_bf16 v[56:59], v[162:165], v[186:189], v[56:59]
	v_mfma_f32_16x16x32_bf16 v[56:59], v[166:169], v[190:193], v[56:59]
	v_mfma_f32_16x16x32_bf16 v[40:43], v[162:165], v[194:197], v[40:43]
	v_mfma_f32_16x16x32_bf16 v[40:43], v[166:169], v[198:201], v[40:43]
	v_mfma_f32_16x16x32_bf16 v[44:47], v[154:157], v[194:197], v[44:47]
	v_mfma_f32_16x16x32_bf16 v[44:47], v[158:161], v[198:201], v[44:47]
	v_mfma_f32_16x16x32_bf16 v[28:31], v[154:157], v[202:205], v[28:31]
	v_mfma_f32_16x16x32_bf16 v[28:31], v[158:161], v[206:209], v[28:31]
	v_mfma_f32_16x16x32_bf16 v[24:27], v[162:165], v[202:205], v[24:27]
	v_mfma_f32_16x16x32_bf16 v[24:27], v[166:169], v[206:209], v[24:27]
	v_mfma_f32_16x16x32_bf16 v[8:11], v[162:165], v[210:213], v[8:11]
	v_mfma_f32_16x16x32_bf16 v[8:11], v[166:169], v[214:217], v[8:11]
	v_mfma_f32_16x16x32_bf16 v[12:15], v[154:157], v[210:213], v[12:15]
	v_mfma_f32_16x16x32_bf16 v[12:15], v[158:161], v[214:217], v[12:15]
	s_setprio 0
	s_setprio 1
	v_mfma_f32_16x16x32_bf16 v[52:55], v[170:173], v[186:189], v[52:55]
	v_mfma_f32_16x16x32_bf16 v[52:55], v[174:177], v[190:193], v[52:55]
	v_mfma_f32_16x16x32_bf16 v[48:51], v[178:181], v[186:189], v[48:51]
	v_mfma_f32_16x16x32_bf16 v[48:51], v[182:185], v[190:193], v[48:51]
	v_mfma_f32_16x16x32_bf16 v[32:35], v[178:181], v[194:197], v[32:35]
	v_mfma_f32_16x16x32_bf16 v[32:35], v[182:185], v[198:201], v[32:35]
	v_mfma_f32_16x16x32_bf16 v[36:39], v[170:173], v[194:197], v[36:39]
	v_mfma_f32_16x16x32_bf16 v[36:39], v[174:177], v[198:201], v[36:39]
	v_mfma_f32_16x16x32_bf16 v[20:23], v[170:173], v[202:205], v[20:23]
	v_mfma_f32_16x16x32_bf16 v[20:23], v[174:177], v[206:209], v[20:23]
	v_mfma_f32_16x16x32_bf16 v[16:19], v[178:181], v[202:205], v[16:19]
	v_mfma_f32_16x16x32_bf16 v[16:19], v[182:185], v[206:209], v[16:19]
	v_mfma_f32_16x16x32_bf16 v[0:3], v[178:181], v[210:213], v[0:3]
	v_mfma_f32_16x16x32_bf16 v[0:3], v[182:185], v[214:217], v[0:3]
	v_mfma_f32_16x16x32_bf16 v[4:7], v[170:173], v[210:213], v[4:7]
	v_mfma_f32_16x16x32_bf16 v[4:7], v[174:177], v[214:217], v[4:7]
	s_setprio 0
	s_barrier
	s_add_i32 s49, s49, 2
	s_add_u32 s24, s24, 0x100
	s_addc_u32 s25, s25, 0
	s_cmp_gt_u32 s49, 29
	s_cbranch_scc0 .LBB0_585
	s_add_u32 s24, s45, 0xffffff00
	s_addc_u32 s25, s46, -1
	s_andn2_b64 vcc, exec, s[4:5]
	s_cbranch_vccnz .LBB0_588
	v_mov_b32_e32 v0, 0
	s_mov_b32 s8, s16
	s_mov_b32 s10, s18
	s_mov_b64 s[12:13], s[22:23]
	s_mov_b32 s41, s44
	v_mov_b32_e32 v1, v0
	v_mov_b32_e32 v2, v0
	v_mov_b32_e32 v3, v0
	v_mov_b32_e32 v4, v0
	v_mov_b32_e32 v5, v0
	v_mov_b32_e32 v6, v0
	v_mov_b32_e32 v7, v0
	v_mov_b32_e32 v16, v0
	v_mov_b32_e32 v17, v0
	v_mov_b32_e32 v18, v0
	v_mov_b32_e32 v19, v0
	v_mov_b32_e32 v20, v0
	v_mov_b32_e32 v21, v0
	v_mov_b32_e32 v22, v0
	v_mov_b32_e32 v23, v0
	v_mov_b32_e32 v32, v0
	v_mov_b32_e32 v33, v0
	v_mov_b32_e32 v34, v0
	v_mov_b32_e32 v35, v0
	v_mov_b32_e32 v36, v0
	v_mov_b32_e32 v37, v0
	v_mov_b32_e32 v38, v0
	v_mov_b32_e32 v39, v0
	v_mov_b32_e32 v48, v0
	v_mov_b32_e32 v49, v0
	v_mov_b32_e32 v50, v0
	v_mov_b32_e32 v51, v0
	v_mov_b32_e32 v52, v0
	v_mov_b32_e32 v53, v0
	v_mov_b32_e32 v54, v0
	v_mov_b32_e32 v55, v0
	v_mov_b32_e32 v8, v0
	v_mov_b32_e32 v9, v0
	v_mov_b32_e32 v10, v0
	v_mov_b32_e32 v11, v0
	v_mov_b32_e32 v12, v0
	v_mov_b32_e32 v13, v0
	v_mov_b32_e32 v14, v0
	v_mov_b32_e32 v15, v0
	v_mov_b32_e32 v24, v0
	v_mov_b32_e32 v25, v0
	v_mov_b32_e32 v26, v0
	v_mov_b32_e32 v27, v0
	v_mov_b32_e32 v28, v0
	v_mov_b32_e32 v29, v0
	v_mov_b32_e32 v30, v0
	v_mov_b32_e32 v31, v0
	v_mov_b32_e32 v40, v0
	v_mov_b32_e32 v41, v0
	v_mov_b32_e32 v42, v0
	v_mov_b32_e32 v43, v0
	v_mov_b32_e32 v44, v0
	v_mov_b32_e32 v45, v0
	v_mov_b32_e32 v46, v0
	v_mov_b32_e32 v47, v0
	v_mov_b32_e32 v56, v0
	v_mov_b32_e32 v57, v0
	v_mov_b32_e32 v58, v0
	v_mov_b32_e32 v59, v0
	v_mov_b32_e32 v60, v0
	v_mov_b32_e32 v61, v0
	v_mov_b32_e32 v62, v0
	v_mov_b32_e32 v63, v0
	v_mov_b32_e32 v64, v0
	v_mov_b32_e32 v65, v0
	v_mov_b32_e32 v66, v0
	v_mov_b32_e32 v67, v0
	v_mov_b32_e32 v68, v0
	v_mov_b32_e32 v69, v0
	v_mov_b32_e32 v70, v0
	v_mov_b32_e32 v71, v0
	v_mov_b32_e32 v80, v0
	v_mov_b32_e32 v81, v0
	v_mov_b32_e32 v82, v0
	v_mov_b32_e32 v83, v0
	v_mov_b32_e32 v84, v0
	v_mov_b32_e32 v85, v0
	v_mov_b32_e32 v86, v0
	v_mov_b32_e32 v87, v0
	v_mov_b32_e32 v96, v0
	v_mov_b32_e32 v97, v0
	v_mov_b32_e32 v98, v0
	v_mov_b32_e32 v99, v0
	v_mov_b32_e32 v100, v0
	v_mov_b32_e32 v101, v0
	v_mov_b32_e32 v102, v0
	v_mov_b32_e32 v103, v0
	v_mov_b32_e32 v112, v0
	v_mov_b32_e32 v113, v0
	v_mov_b32_e32 v114, v0
	v_mov_b32_e32 v115, v0
	v_mov_b32_e32 v116, v0
	v_mov_b32_e32 v117, v0
	v_mov_b32_e32 v118, v0
	v_mov_b32_e32 v119, v0
	v_mov_b32_e32 v72, v0
	v_mov_b32_e32 v73, v0
	v_mov_b32_e32 v74, v0
	v_mov_b32_e32 v75, v0
	v_mov_b32_e32 v76, v0
	v_mov_b32_e32 v77, v0
	v_mov_b32_e32 v78, v0
	v_mov_b32_e32 v79, v0
	v_mov_b32_e32 v88, v0
	v_mov_b32_e32 v89, v0
	v_mov_b32_e32 v90, v0
	v_mov_b32_e32 v91, v0
	v_mov_b32_e32 v92, v0
	v_mov_b32_e32 v93, v0
	v_mov_b32_e32 v94, v0
	v_mov_b32_e32 v95, v0
	v_mov_b32_e32 v104, v0
	v_mov_b32_e32 v105, v0
	v_mov_b32_e32 v106, v0
	v_mov_b32_e32 v107, v0
	v_mov_b32_e32 v108, v0
	v_mov_b32_e32 v109, v0
	v_mov_b32_e32 v110, v0
	v_mov_b32_e32 v111, v0
	v_mov_b32_e32 v120, v0
	v_mov_b32_e32 v121, v0
	v_mov_b32_e32 v122, v0
	v_mov_b32_e32 v123, v0
	v_mov_b32_e32 v124, v0
	v_mov_b32_e32 v125, v0
	v_mov_b32_e32 v126, v0
	v_mov_b32_e32 v127, v0
	s_andn2_b64 vcc, exec, s[0:1]
	s_cbranch_vccnz .LBB0_589
	s_branch .LBB0_590

.LBB0_671:
	ds_read_b128 v[156:159], v151
	ds_read_b128 v[160:163], v151 offset:1024
	ds_read_b128 v[164:167], v151 offset:2048
	ds_read_b128 v[168:171], v151 offset:3072
	ds_read_b128 v[172:175], v152
	ds_read_b128 v[176:179], v152 offset:1024
	ds_read_b128 v[180:183], v152 offset:2048
	ds_read_b128 v[184:187], v152 offset:3072
	s_add_u32 s28, s26, 0xfff80080
	s_addc_u32 s29, s27, -1
	s_cmp_eq_u32 s53, 28
	s_cselect_b32 s31, s19, s29
	s_cselect_b32 s30, s49, s28
	s_cselect_b32 s29, s17, s52
	s_cselect_b32 s28, s50, s51
	v_lshl_add_u64 v[146:147], s[26:27], 0, v[138:139]
	s_add_i32 m0, s25, 0xc000
	ds_read_b128 v[188:191], v153
	ds_read_b128 v[192:195], v153 offset:1024
	ds_read_b128 v[196:199], v153 offset:2048
	ds_read_b128 v[200:203], v153 offset:3072
	ds_read_b128 v[204:207], v153 offset:4096
	ds_read_b128 v[208:211], v153 offset:5120
	ds_read_b128 v[212:215], v153 offset:6144
	ds_read_b128 v[216:219], v153 offset:7168
	global_load_lds_dwordx4 v[146:147], off
	v_lshl_add_u64 v[146:147], s[26:27], 0, v[140:141]
	s_add_i32 m0, s25, 0xe000
	s_nop 0
	global_load_lds_dwordx4 v[146:147], off
	s_waitcnt vmcnt(8)
	s_waitcnt lgkmcnt(0)
	s_barrier
	s_setprio 1
	s_waitcnt lgkmcnt(0)
	v_mfma_f32_16x16x32_bf16 v[116:119], v[156:159], v[188:191], v[116:119]
	v_mfma_f32_16x16x32_bf16 v[116:119], v[160:163], v[192:195], v[116:119]
	v_mfma_f32_16x16x32_bf16 v[112:115], v[164:167], v[188:191], v[112:115]
	v_mfma_f32_16x16x32_bf16 v[112:115], v[168:171], v[192:195], v[112:115]
	v_mfma_f32_16x16x32_bf16 v[96:99], v[164:167], v[196:199], v[96:99]
	v_mfma_f32_16x16x32_bf16 v[96:99], v[168:171], v[200:203], v[96:99]
	v_mfma_f32_16x16x32_bf16 v[100:103], v[156:159], v[196:199], v[100:103]
	v_mfma_f32_16x16x32_bf16 v[100:103], v[160:163], v[200:203], v[100:103]
	v_mfma_f32_16x16x32_bf16 v[84:87], v[156:159], v[204:207], v[84:87]
	v_mfma_f32_16x16x32_bf16 v[84:87], v[160:163], v[208:211], v[84:87]
	v_mfma_f32_16x16x32_bf16 v[80:83], v[164:167], v[204:207], v[80:83]
	v_mfma_f32_16x16x32_bf16 v[80:83], v[168:171], v[208:211], v[80:83]
	v_mfma_f32_16x16x32_bf16 v[64:67], v[164:167], v[212:215], v[64:67]
	v_mfma_f32_16x16x32_bf16 v[64:67], v[168:171], v[216:219], v[64:67]
	v_mfma_f32_16x16x32_bf16 v[68:71], v[156:159], v[212:215], v[68:71]
	v_mfma_f32_16x16x32_bf16 v[68:71], v[160:163], v[216:219], v[68:71]
	s_setprio 0
	s_setprio 1
	v_mfma_f32_16x16x32_bf16 v[124:127], v[172:175], v[188:191], v[124:127]
	v_mfma_f32_16x16x32_bf16 v[124:127], v[176:179], v[192:195], v[124:127]
	v_mfma_f32_16x16x32_bf16 v[120:123], v[180:183], v[188:191], v[120:123]
	v_mfma_f32_16x16x32_bf16 v[120:123], v[184:187], v[192:195], v[120:123]
	v_mfma_f32_16x16x32_bf16 v[104:107], v[180:183], v[196:199], v[104:107]
	v_mfma_f32_16x16x32_bf16 v[104:107], v[184:187], v[200:203], v[104:107]
	v_mfma_f32_16x16x32_bf16 v[108:111], v[172:175], v[196:199], v[108:111]
	v_mfma_f32_16x16x32_bf16 v[108:111], v[176:179], v[200:203], v[108:111]
	v_mfma_f32_16x16x32_bf16 v[92:95], v[172:175], v[204:207], v[92:95]
	v_mfma_f32_16x16x32_bf16 v[92:95], v[176:179], v[208:211], v[92:95]
	v_mfma_f32_16x16x32_bf16 v[88:91], v[180:183], v[204:207], v[88:91]
	v_mfma_f32_16x16x32_bf16 v[88:91], v[184:187], v[208:211], v[88:91]
	v_mfma_f32_16x16x32_bf16 v[72:75], v[180:183], v[212:215], v[72:75]
	v_mfma_f32_16x16x32_bf16 v[72:75], v[184:187], v[216:219], v[72:75]
	v_mfma_f32_16x16x32_bf16 v[76:79], v[172:175], v[212:215], v[76:79]
	v_mfma_f32_16x16x32_bf16 v[76:79], v[176:179], v[216:219], v[76:79]
	s_setprio 0
	s_barrier
	s_add_i32 s54, s46, s36
	v_lshl_add_u64 v[146:147], s[28:29], 0, v[134:135]
	s_mov_b32 m0, s54
	ds_read_b128 v[188:191], v153 offset:16384
	ds_read_b128 v[192:195], v153 offset:17408
	ds_read_b128 v[196:199], v153 offset:18432
	ds_read_b128 v[200:203], v153 offset:19456
	ds_read_b128 v[204:207], v153 offset:20480
	ds_read_b128 v[208:211], v153 offset:21504
	ds_read_b128 v[212:215], v153 offset:22528
	ds_read_b128 v[216:219], v153 offset:23552
	global_load_lds_dwordx4 v[146:147], off
	s_add_i32 m0, s54, 0x2000
	s_add_u32 s54, s28, 0x80000
	v_lshl_add_u64 v[220:221], s[28:29], 0, v[130:131]
	s_addc_u32 s55, s29, 0
	s_add_i32 s56, s47, s36
	global_load_lds_dwordx4 v[220:221], off
	v_lshl_add_u64 v[222:223], s[54:55], 0, v[134:135]
	s_mov_b32 m0, s56
	v_lshl_add_u64 v[224:225], s[30:31], 0, v[132:133]
	global_load_lds_dwordx4 v[222:223], off
	v_lshl_add_u64 v[222:223], s[54:55], 0, v[130:131]
	s_add_i32 m0, s56, 0x2000
	s_nop 0
	global_load_lds_dwordx4 v[222:223], off
	v_lshl_add_u64 v[222:223], s[30:31], 0, v[136:137]
	s_mov_b32 m0, s25
	s_nop 0
	global_load_lds_dwordx4 v[222:223], off
	s_mov_b32 m0, s39
	s_nop 0
	global_load_lds_dwordx4 v[224:225], off
	s_waitcnt vmcnt(8)
	s_waitcnt lgkmcnt(0)
	s_barrier
	s_setprio 1
	s_waitcnt lgkmcnt(0)
	v_mfma_f32_16x16x32_bf16 v[52:55], v[156:159], v[188:191], v[52:55]
	v_mfma_f32_16x16x32_bf16 v[52:55], v[160:163], v[192:195], v[52:55]
	v_mfma_f32_16x16x32_bf16 v[48:51], v[164:167], v[188:191], v[48:51]
	v_mfma_f32_16x16x32_bf16 v[48:51], v[168:171], v[192:195], v[48:51]
	v_mfma_f32_16x16x32_bf16 v[32:35], v[164:167], v[196:199], v[32:35]
	v_mfma_f32_16x16x32_bf16 v[32:35], v[168:171], v[200:203], v[32:35]
	v_mfma_f32_16x16x32_bf16 v[36:39], v[156:159], v[196:199], v[36:39]
	v_mfma_f32_16x16x32_bf16 v[36:39], v[160:163], v[200:203], v[36:39]
	v_mfma_f32_16x16x32_bf16 v[20:23], v[156:159], v[204:207], v[20:23]
	v_mfma_f32_16x16x32_bf16 v[20:23], v[160:163], v[208:211], v[20:23]
	v_mfma_f32_16x16x32_bf16 v[16:19], v[164:167], v[204:207], v[16:19]
	v_mfma_f32_16x16x32_bf16 v[16:19], v[168:171], v[208:211], v[16:19]
	v_mfma_f32_16x16x32_bf16 v[0:3], v[164:167], v[212:215], v[0:3]
	v_mfma_f32_16x16x32_bf16 v[0:3], v[168:171], v[216:219], v[0:3]
	v_mfma_f32_16x16x32_bf16 v[8:11], v[156:159], v[212:215], v[8:11]
	v_mfma_f32_16x16x32_bf16 v[8:11], v[160:163], v[216:219], v[8:11]
	s_setprio 0
	s_setprio 1
	v_mfma_f32_16x16x32_bf16 v[60:63], v[172:175], v[188:191], v[60:63]
	v_mfma_f32_16x16x32_bf16 v[60:63], v[176:179], v[192:195], v[60:63]
	v_mfma_f32_16x16x32_bf16 v[56:59], v[180:183], v[188:191], v[56:59]
	v_mfma_f32_16x16x32_bf16 v[56:59], v[184:187], v[192:195], v[56:59]
	v_mfma_f32_16x16x32_bf16 v[40:43], v[180:183], v[196:199], v[40:43]
	v_mfma_f32_16x16x32_bf16 v[40:43], v[184:187], v[200:203], v[40:43]
	v_mfma_f32_16x16x32_bf16 v[44:47], v[172:175], v[196:199], v[44:47]
	v_mfma_f32_16x16x32_bf16 v[44:47], v[176:179], v[200:203], v[44:47]
	v_mfma_f32_16x16x32_bf16 v[28:31], v[172:175], v[204:207], v[28:31]
	v_mfma_f32_16x16x32_bf16 v[28:31], v[176:179], v[208:211], v[28:31]
	v_mfma_f32_16x16x32_bf16 v[24:27], v[180:183], v[204:207], v[24:27]
	v_mfma_f32_16x16x32_bf16 v[24:27], v[184:187], v[208:211], v[24:27]
	v_mfma_f32_16x16x32_bf16 v[4:7], v[180:183], v[212:215], v[4:7]
	v_mfma_f32_16x16x32_bf16 v[4:7], v[184:187], v[216:219], v[4:7]
	v_mfma_f32_16x16x32_bf16 v[12:15], v[172:175], v[212:215], v[12:15]
	v_mfma_f32_16x16x32_bf16 v[12:15], v[176:179], v[216:219], v[12:15]
	s_setprio 0
	s_barrier
	s_add_i32 s54, 0, 0x18000
	v_add_u32_e32 v155, s54, v149
	s_add_i32 s55, 0, 0x1c000
	ds_read_b128 v[156:159], v155
	ds_read_b128 v[160:163], v155 offset:1024
	ds_read_b128 v[164:167], v155 offset:2048
	ds_read_b128 v[168:171], v155 offset:3072
	v_add_u32_e32 v155, s55, v149
	ds_read_b128 v[172:175], v155
	ds_read_b128 v[176:179], v155 offset:1024
	ds_read_b128 v[180:183], v155 offset:2048
	ds_read_b128 v[184:187], v155 offset:3072
	s_add_u32 s30, s30, 0x80000
	s_addc_u32 s31, s31, 0
	s_mov_b32 m0, s40
	v_lshl_add_u64 v[226:227], s[30:31], 0, v[136:137]
	ds_read_b128 v[188:191], v153 offset:32768
	ds_read_b128 v[192:195], v153 offset:33792
	ds_read_b128 v[196:199], v153 offset:34816
	ds_read_b128 v[200:203], v153 offset:35840
	ds_read_b128 v[204:207], v153 offset:36864
	ds_read_b128 v[208:211], v153 offset:37888
	ds_read_b128 v[212:215], v153 offset:38912
	ds_read_b128 v[216:219], v153 offset:39936
	global_load_lds_dwordx4 v[226:227], off
	v_lshl_add_u64 v[226:227], s[30:31], 0, v[132:133]
	s_mov_b32 m0, s41
	s_nop 0
	global_load_lds_dwordx4 v[226:227], off
	s_waitcnt vmcnt(8)
	s_waitcnt lgkmcnt(0)
	s_barrier
	s_setprio 1
	s_waitcnt lgkmcnt(0)
	v_mfma_f32_16x16x32_bf16 v[116:119], v[156:159], v[188:191], v[116:119]
	v_mfma_f32_16x16x32_bf16 v[116:119], v[160:163], v[192:195], v[116:119]
	v_mfma_f32_16x16x32_bf16 v[112:115], v[164:167], v[188:191], v[112:115]
	v_mfma_f32_16x16x32_bf16 v[112:115], v[168:171], v[192:195], v[112:115]
	v_mfma_f32_16x16x32_bf16 v[96:99], v[164:167], v[196:199], v[96:99]
	v_mfma_f32_16x16x32_bf16 v[96:99], v[168:171], v[200:203], v[96:99]
	v_mfma_f32_16x16x32_bf16 v[100:103], v[156:159], v[196:199], v[100:103]
	v_mfma_f32_16x16x32_bf16 v[100:103], v[160:163], v[200:203], v[100:103]
	v_mfma_f32_16x16x32_bf16 v[84:87], v[156:159], v[204:207], v[84:87]
	v_mfma_f32_16x16x32_bf16 v[84:87], v[160:163], v[208:211], v[84:87]
	v_mfma_f32_16x16x32_bf16 v[80:83], v[164:167], v[204:207], v[80:83]
	v_mfma_f32_16x16x32_bf16 v[80:83], v[168:171], v[208:211], v[80:83]
	v_mfma_f32_16x16x32_bf16 v[64:67], v[164:167], v[212:215], v[64:67]
	v_mfma_f32_16x16x32_bf16 v[64:67], v[168:171], v[216:219], v[64:67]
	v_mfma_f32_16x16x32_bf16 v[68:71], v[156:159], v[212:215], v[68:71]
	v_mfma_f32_16x16x32_bf16 v[68:71], v[160:163], v[216:219], v[68:71]
	s_setprio 0
	s_setprio 1
	v_mfma_f32_16x16x32_bf16 v[124:127], v[172:175], v[188:191], v[124:127]
	v_mfma_f32_16x16x32_bf16 v[124:127], v[176:179], v[192:195], v[124:127]
	v_mfma_f32_16x16x32_bf16 v[120:123], v[180:183], v[188:191], v[120:123]
	v_mfma_f32_16x16x32_bf16 v[120:123], v[184:187], v[192:195], v[120:123]
	v_mfma_f32_16x16x32_bf16 v[104:107], v[180:183], v[196:199], v[104:107]
	v_mfma_f32_16x16x32_bf16 v[104:107], v[184:187], v[200:203], v[104:107]
	v_mfma_f32_16x16x32_bf16 v[108:111], v[172:175], v[196:199], v[108:111]
	v_mfma_f32_16x16x32_bf16 v[108:111], v[176:179], v[200:203], v[108:111]
	v_mfma_f32_16x16x32_bf16 v[92:95], v[172:175], v[204:207], v[92:95]
	v_mfma_f32_16x16x32_bf16 v[92:95], v[176:179], v[208:211], v[92:95]
	v_mfma_f32_16x16x32_bf16 v[88:91], v[180:183], v[204:207], v[88:91]
	v_mfma_f32_16x16x32_bf16 v[88:91], v[184:187], v[208:211], v[88:91]
	v_mfma_f32_16x16x32_bf16 v[72:75], v[180:183], v[212:215], v[72:75]
	v_mfma_f32_16x16x32_bf16 v[72:75], v[184:187], v[216:219], v[72:75]
	v_mfma_f32_16x16x32_bf16 v[76:79], v[172:175], v[212:215], v[76:79]
	v_mfma_f32_16x16x32_bf16 v[76:79], v[176:179], v[216:219], v[76:79]
	s_setprio 0
	s_barrier
	s_add_i32 s30, s54, s36
	v_lshl_add_u64 v[146:147], v[146:147], 0, s[12:13]
	s_mov_b32 m0, s30
	ds_read_b128 v[188:191], v153 offset:49152
	ds_read_b128 v[192:195], v153 offset:50176
	ds_read_b128 v[196:199], v153 offset:51200
	ds_read_b128 v[200:203], v153 offset:52224
	ds_read_b128 v[204:207], v153 offset:53248
	ds_read_b128 v[208:211], v153 offset:54272
	ds_read_b128 v[212:215], v153 offset:55296
	ds_read_b128 v[216:219], v153 offset:56320
	global_load_lds_dwordx4 v[146:147], off
	s_add_i32 m0, s30, 0x2000
	s_add_u32 s28, s28, 0x80080
	v_lshl_add_u64 v[146:147], v[220:221], 0, s[12:13]
	s_addc_u32 s29, s29, 0
	s_add_i32 s30, s55, s36
	global_load_lds_dwordx4 v[146:147], off
	v_lshl_add_u64 v[146:147], s[28:29], 0, v[134:135]
	s_mov_b32 m0, s30
	s_nop 0
	global_load_lds_dwordx4 v[146:147], off
	v_lshl_add_u64 v[146:147], s[28:29], 0, v[130:131]
	s_add_i32 m0, s30, 0x2000
	s_nop 0
	global_load_lds_dwordx4 v[146:147], off
	v_lshl_add_u64 v[146:147], v[222:223], 0, s[12:13]
	s_mov_b32 m0, s43
	s_nop 0
	global_load_lds_dwordx4 v[146:147], off
	v_lshl_add_u64 v[146:147], v[224:225], 0, s[12:13]
	s_mov_b32 m0, s44
	s_nop 0
	global_load_lds_dwordx4 v[146:147], off
	s_waitcnt vmcnt(8)
	s_waitcnt lgkmcnt(0)
	s_barrier
	s_setprio 1
	s_waitcnt lgkmcnt(0)
	v_mfma_f32_16x16x32_bf16 v[52:55], v[156:159], v[188:191], v[52:55]
	v_mfma_f32_16x16x32_bf16 v[52:55], v[160:163], v[192:195], v[52:55]
	v_mfma_f32_16x16x32_bf16 v[48:51], v[164:167], v[188:191], v[48:51]
	v_mfma_f32_16x16x32_bf16 v[48:51], v[168:171], v[192:195], v[48:51]
	v_mfma_f32_16x16x32_bf16 v[32:35], v[164:167], v[196:199], v[32:35]
	v_mfma_f32_16x16x32_bf16 v[32:35], v[168:171], v[200:203], v[32:35]
	v_mfma_f32_16x16x32_bf16 v[36:39], v[156:159], v[196:199], v[36:39]
	v_mfma_f32_16x16x32_bf16 v[36:39], v[160:163], v[200:203], v[36:39]
	v_mfma_f32_16x16x32_bf16 v[20:23], v[156:159], v[204:207], v[20:23]
	v_mfma_f32_16x16x32_bf16 v[20:23], v[160:163], v[208:211], v[20:23]
	v_mfma_f32_16x16x32_bf16 v[16:19], v[164:167], v[204:207], v[16:19]
	v_mfma_f32_16x16x32_bf16 v[16:19], v[168:171], v[208:211], v[16:19]
	v_mfma_f32_16x16x32_bf16 v[0:3], v[164:167], v[212:215], v[0:3]
	v_mfma_f32_16x16x32_bf16 v[0:3], v[168:171], v[216:219], v[0:3]
	v_mfma_f32_16x16x32_bf16 v[8:11], v[156:159], v[212:215], v[8:11]
	v_mfma_f32_16x16x32_bf16 v[8:11], v[160:163], v[216:219], v[8:11]
	s_setprio 0
	s_setprio 1
	v_mfma_f32_16x16x32_bf16 v[60:63], v[172:175], v[188:191], v[60:63]
	v_mfma_f32_16x16x32_bf16 v[60:63], v[176:179], v[192:195], v[60:63]
	v_mfma_f32_16x16x32_bf16 v[56:59], v[180:183], v[188:191], v[56:59]
	v_mfma_f32_16x16x32_bf16 v[56:59], v[184:187], v[192:195], v[56:59]
	v_mfma_f32_16x16x32_bf16 v[40:43], v[180:183], v[196:199], v[40:43]
	v_mfma_f32_16x16x32_bf16 v[40:43], v[184:187], v[200:203], v[40:43]
	v_mfma_f32_16x16x32_bf16 v[44:47], v[172:175], v[196:199], v[44:47]
	v_mfma_f32_16x16x32_bf16 v[44:47], v[176:179], v[200:203], v[44:47]
	v_mfma_f32_16x16x32_bf16 v[28:31], v[172:175], v[204:207], v[28:31]
	v_mfma_f32_16x16x32_bf16 v[28:31], v[176:179], v[208:211], v[28:31]
	v_mfma_f32_16x16x32_bf16 v[24:27], v[180:183], v[204:207], v[24:27]
	v_mfma_f32_16x16x32_bf16 v[24:27], v[184:187], v[208:211], v[24:27]
	v_mfma_f32_16x16x32_bf16 v[4:7], v[180:183], v[212:215], v[4:7]
	v_mfma_f32_16x16x32_bf16 v[4:7], v[184:187], v[216:219], v[4:7]
	v_mfma_f32_16x16x32_bf16 v[12:15], v[172:175], v[212:215], v[12:15]
	v_mfma_f32_16x16x32_bf16 v[12:15], v[176:179], v[216:219], v[12:15]
	s_setprio 0
	s_barrier
	s_add_i32 s53, s53, 2
	s_add_u32 s26, s26, 0x100
	s_addc_u32 s27, s27, 0
	s_add_u32 s51, s51, 0x100
	s_addc_u32 s52, s52, 0
	s_cmp_gt_u32 s53, 29
	s_cbranch_scc0 .LBB0_671
	s_and_b64 vcc, exec, s[14:15]
	s_cbranch_vccz .LBB0_674
	s_barrier

.LBB0_849:
	v_add_u32_e32 v164, s40, v129
	v_add_u32_e32 v173, s41, v129
	s_add_u32 s22, s14, s20
	ds_read_b128 v[152:155], v164
	ds_read_b128 v[156:159], v164 offset:1024
	ds_read_b128 v[160:163], v164 offset:2048
	ds_read_b128 v[164:167], v164 offset:3072
	ds_read_b128 v[168:171], v173
	ds_read_b128 v[174:177], v173 offset:1024
	ds_read_b128 v[178:181], v173 offset:2048
	ds_read_b128 v[182:185], v173 offset:3072
	s_addc_u32 s23, s15, s21
	s_add_u32 s22, s22, 0x100
	s_addc_u32 s23, s23, 0
	s_add_u32 s48, s45, s20
	s_addc_u32 s49, s46, s21
	s_cmpk_eq_i32 s20, 0x2b00
	s_cselect_b32 s25, s19, s23
	s_cselect_b32 s24, s18, s22
	s_cselect_b32 s23, s7, s49
	s_cselect_b32 s22, s6, s48
	v_lshl_add_u64 v[218:219], v[146:147], 0, s[20:21]
	s_add_i32 m0, s33, 0xc000
	ds_read_b128 v[186:189], v151
	ds_read_b128 v[190:193], v151 offset:1024
	ds_read_b128 v[194:197], v151 offset:2048
	ds_read_b128 v[198:201], v151 offset:3072
	ds_read_b128 v[202:205], v151 offset:4096
	ds_read_b128 v[206:209], v151 offset:5120
	ds_read_b128 v[210:213], v151 offset:6144
	ds_read_b128 v[214:217], v151 offset:7168
	global_load_lds_dwordx4 v[218:219], off
	v_lshl_add_u64 v[218:219], v[148:149], 0, s[20:21]
	s_add_i32 m0, s33, 0xe000
	s_nop 0
	global_load_lds_dwordx4 v[218:219], off
	s_waitcnt vmcnt(8)
	s_waitcnt lgkmcnt(0)
	s_barrier
	s_setprio 1
	s_waitcnt lgkmcnt(0)
	v_mfma_f32_16x16x32_bf16 v[124:127], v[152:155], v[186:189], v[124:127]
	v_mfma_f32_16x16x32_bf16 v[124:127], v[156:159], v[190:193], v[124:127]
	v_mfma_f32_16x16x32_bf16 v[120:123], v[160:163], v[186:189], v[120:123]
	v_mfma_f32_16x16x32_bf16 v[120:123], v[164:167], v[190:193], v[120:123]
	v_mfma_f32_16x16x32_bf16 v[104:107], v[160:163], v[194:197], v[104:107]
	v_mfma_f32_16x16x32_bf16 v[104:107], v[164:167], v[198:201], v[104:107]
	v_mfma_f32_16x16x32_bf16 v[108:111], v[152:155], v[194:197], v[108:111]
	v_mfma_f32_16x16x32_bf16 v[108:111], v[156:159], v[198:201], v[108:111]
	v_mfma_f32_16x16x32_bf16 v[92:95], v[152:155], v[202:205], v[92:95]
	v_mfma_f32_16x16x32_bf16 v[92:95], v[156:159], v[206:209], v[92:95]
	v_mfma_f32_16x16x32_bf16 v[88:91], v[160:163], v[202:205], v[88:91]
	v_mfma_f32_16x16x32_bf16 v[88:91], v[164:167], v[206:209], v[88:91]
	v_mfma_f32_16x16x32_bf16 v[72:75], v[160:163], v[210:213], v[72:75]
	v_mfma_f32_16x16x32_bf16 v[72:75], v[164:167], v[214:217], v[72:75]
	v_mfma_f32_16x16x32_bf16 v[76:79], v[152:155], v[210:213], v[76:79]
	v_mfma_f32_16x16x32_bf16 v[76:79], v[156:159], v[214:217], v[76:79]
	s_setprio 0
	s_setprio 1
	v_mfma_f32_16x16x32_bf16 v[116:119], v[168:171], v[186:189], v[116:119]
	v_mfma_f32_16x16x32_bf16 v[116:119], v[174:177], v[190:193], v[116:119]
	v_mfma_f32_16x16x32_bf16 v[112:115], v[178:181], v[186:189], v[112:115]
	v_mfma_f32_16x16x32_bf16 v[112:115], v[182:185], v[190:193], v[112:115]
	v_mfma_f32_16x16x32_bf16 v[96:99], v[178:181], v[194:197], v[96:99]
	v_mfma_f32_16x16x32_bf16 v[96:99], v[182:185], v[198:201], v[96:99]
	v_mfma_f32_16x16x32_bf16 v[100:103], v[168:171], v[194:197], v[100:103]
	v_mfma_f32_16x16x32_bf16 v[100:103], v[174:177], v[198:201], v[100:103]
	v_mfma_f32_16x16x32_bf16 v[84:87], v[168:171], v[202:205], v[84:87]
	v_mfma_f32_16x16x32_bf16 v[84:87], v[174:177], v[206:209], v[84:87]
	v_mfma_f32_16x16x32_bf16 v[80:83], v[178:181], v[202:205], v[80:83]
	v_mfma_f32_16x16x32_bf16 v[80:83], v[182:185], v[206:209], v[80:83]
	v_mfma_f32_16x16x32_bf16 v[64:67], v[178:181], v[210:213], v[64:67]
	v_mfma_f32_16x16x32_bf16 v[64:67], v[182:185], v[214:217], v[64:67]
	v_mfma_f32_16x16x32_bf16 v[68:71], v[168:171], v[210:213], v[68:71]
	v_mfma_f32_16x16x32_bf16 v[68:71], v[174:177], v[214:217], v[68:71]
	s_setprio 0
	s_barrier
	s_add_i32 s48, s40, s31
	v_lshl_add_u64 v[218:219], s[22:23], 0, v[132:133]
	s_mov_b32 m0, s48
	ds_read_b128 v[186:189], v151 offset:16384
	ds_read_b128 v[190:193], v151 offset:17408
	ds_read_b128 v[194:197], v151 offset:18432
	ds_read_b128 v[198:201], v151 offset:19456
	ds_read_b128 v[202:205], v151 offset:20480
	ds_read_b128 v[206:209], v151 offset:21504
	ds_read_b128 v[210:213], v151 offset:22528
	ds_read_b128 v[214:217], v151 offset:23552
	global_load_lds_dwordx4 v[218:219], off
	s_add_i32 m0, s48, 0x2000
	s_add_u32 s48, s22, 0x160000
	v_lshl_add_u64 v[220:221], s[22:23], 0, v[136:137]
	s_addc_u32 s49, s23, 0
	s_add_i32 s50, s41, s31
	global_load_lds_dwordx4 v[220:221], off
	v_lshl_add_u64 v[222:223], s[48:49], 0, v[132:133]
	s_mov_b32 m0, s50
	v_lshl_add_u64 v[224:225], s[24:25], 0, v[134:135]
	global_load_lds_dwordx4 v[222:223], off
	v_lshl_add_u64 v[222:223], s[48:49], 0, v[136:137]
	s_add_i32 m0, s50, 0x2000
	s_nop 0
	global_load_lds_dwordx4 v[222:223], off
	v_lshl_add_u64 v[222:223], s[24:25], 0, v[130:131]
	s_mov_b32 m0, s33
	s_nop 0
	global_load_lds_dwordx4 v[222:223], off
	s_mov_b32 m0, s34
	s_nop 0
	global_load_lds_dwordx4 v[224:225], off
	s_waitcnt vmcnt(8)
	s_waitcnt lgkmcnt(0)
	s_barrier
	s_setprio 1
	s_waitcnt lgkmcnt(0)
	v_mfma_f32_16x16x32_bf16 v[60:63], v[152:155], v[186:189], v[60:63]
	v_mfma_f32_16x16x32_bf16 v[60:63], v[156:159], v[190:193], v[60:63]
	v_mfma_f32_16x16x32_bf16 v[56:59], v[160:163], v[186:189], v[56:59]
	v_mfma_f32_16x16x32_bf16 v[56:59], v[164:167], v[190:193], v[56:59]
	v_mfma_f32_16x16x32_bf16 v[40:43], v[160:163], v[194:197], v[40:43]
	v_mfma_f32_16x16x32_bf16 v[40:43], v[164:167], v[198:201], v[40:43]
	v_mfma_f32_16x16x32_bf16 v[44:47], v[152:155], v[194:197], v[44:47]
	v_mfma_f32_16x16x32_bf16 v[44:47], v[156:159], v[198:201], v[44:47]
	v_mfma_f32_16x16x32_bf16 v[28:31], v[152:155], v[202:205], v[28:31]
	v_mfma_f32_16x16x32_bf16 v[28:31], v[156:159], v[206:209], v[28:31]
	v_mfma_f32_16x16x32_bf16 v[24:27], v[160:163], v[202:205], v[24:27]
	v_mfma_f32_16x16x32_bf16 v[24:27], v[164:167], v[206:209], v[24:27]
	v_mfma_f32_16x16x32_bf16 v[8:11], v[160:163], v[210:213], v[8:11]
	v_mfma_f32_16x16x32_bf16 v[8:11], v[164:167], v[214:217], v[8:11]
	v_mfma_f32_16x16x32_bf16 v[12:15], v[152:155], v[210:213], v[12:15]
	v_mfma_f32_16x16x32_bf16 v[12:15], v[156:159], v[214:217], v[12:15]
	s_setprio 0
	s_setprio 1
	v_mfma_f32_16x16x32_bf16 v[52:55], v[168:171], v[186:189], v[52:55]
	v_mfma_f32_16x16x32_bf16 v[52:55], v[174:177], v[190:193], v[52:55]
	v_mfma_f32_16x16x32_bf16 v[48:51], v[178:181], v[186:189], v[48:51]
	v_mfma_f32_16x16x32_bf16 v[48:51], v[182:185], v[190:193], v[48:51]
	v_mfma_f32_16x16x32_bf16 v[32:35], v[178:181], v[194:197], v[32:35]
	v_mfma_f32_16x16x32_bf16 v[32:35], v[182:185], v[198:201], v[32:35]
	v_mfma_f32_16x16x32_bf16 v[36:39], v[168:171], v[194:197], v[36:39]
	v_mfma_f32_16x16x32_bf16 v[36:39], v[174:177], v[198:201], v[36:39]
	v_mfma_f32_16x16x32_bf16 v[20:23], v[168:171], v[202:205], v[20:23]
	v_mfma_f32_16x16x32_bf16 v[20:23], v[174:177], v[206:209], v[20:23]
	v_mfma_f32_16x16x32_bf16 v[16:19], v[178:181], v[202:205], v[16:19]
	v_mfma_f32_16x16x32_bf16 v[16:19], v[182:185], v[206:209], v[16:19]
	v_mfma_f32_16x16x32_bf16 v[0:3], v[178:181], v[210:213], v[0:3]
	v_mfma_f32_16x16x32_bf16 v[0:3], v[182:185], v[214:217], v[0:3]
	v_mfma_f32_16x16x32_bf16 v[4:7], v[168:171], v[210:213], v[4:7]
	v_mfma_f32_16x16x32_bf16 v[4:7], v[174:177], v[214:217], v[4:7]
	s_setprio 0
	s_barrier
	s_add_i32 s48, 0, 0x18000
	s_add_i32 s49, 0, 0x1c000
	v_add_u32_e32 v164, s48, v129
	v_add_u32_e32 v173, s49, v129
	ds_read_b128 v[152:155], v164
	ds_read_b128 v[156:159], v164 offset:1024
	ds_read_b128 v[160:163], v164 offset:2048
	ds_read_b128 v[164:167], v164 offset:3072
	ds_read_b128 v[168:171], v173
	ds_read_b128 v[174:177], v173 offset:1024
	ds_read_b128 v[178:181], v173 offset:2048
	ds_read_b128 v[182:185], v173 offset:3072
	s_add_u32 s24, s24, 0x160000
	s_addc_u32 s25, s25, 0
	s_mov_b32 m0, s35
	v_lshl_add_u64 v[226:227], s[24:25], 0, v[130:131]
	ds_read_b128 v[186:189], v151 offset:32768
	ds_read_b128 v[190:193], v151 offset:33792
	ds_read_b128 v[194:197], v151 offset:34816
	ds_read_b128 v[198:201], v151 offset:35840
	ds_read_b128 v[202:205], v151 offset:36864
	ds_read_b128 v[206:209], v151 offset:37888
	ds_read_b128 v[210:213], v151 offset:38912
	ds_read_b128 v[214:217], v151 offset:39936
	global_load_lds_dwordx4 v[226:227], off
	v_lshl_add_u64 v[226:227], s[24:25], 0, v[134:135]
	s_mov_b32 m0, s36
	s_nop 0
	global_load_lds_dwordx4 v[226:227], off
	s_waitcnt vmcnt(8)
	s_waitcnt lgkmcnt(0)
	s_barrier
	s_setprio 1
	s_waitcnt lgkmcnt(0)
	v_mfma_f32_16x16x32_bf16 v[124:127], v[152:155], v[186:189], v[124:127]
	v_mfma_f32_16x16x32_bf16 v[124:127], v[156:159], v[190:193], v[124:127]
	v_mfma_f32_16x16x32_bf16 v[120:123], v[160:163], v[186:189], v[120:123]
	v_mfma_f32_16x16x32_bf16 v[120:123], v[164:167], v[190:193], v[120:123]
	v_mfma_f32_16x16x32_bf16 v[104:107], v[160:163], v[194:197], v[104:107]
	v_mfma_f32_16x16x32_bf16 v[104:107], v[164:167], v[198:201], v[104:107]
	v_mfma_f32_16x16x32_bf16 v[108:111], v[152:155], v[194:197], v[108:111]
	v_mfma_f32_16x16x32_bf16 v[108:111], v[156:159], v[198:201], v[108:111]
	v_mfma_f32_16x16x32_bf16 v[92:95], v[152:155], v[202:205], v[92:95]
	v_mfma_f32_16x16x32_bf16 v[92:95], v[156:159], v[206:209], v[92:95]
	v_mfma_f32_16x16x32_bf16 v[88:91], v[160:163], v[202:205], v[88:91]
	v_mfma_f32_16x16x32_bf16 v[88:91], v[164:167], v[206:209], v[88:91]
	v_mfma_f32_16x16x32_bf16 v[72:75], v[160:163], v[210:213], v[72:75]
	v_mfma_f32_16x16x32_bf16 v[72:75], v[164:167], v[214:217], v[72:75]
	v_mfma_f32_16x16x32_bf16 v[76:79], v[152:155], v[210:213], v[76:79]
	v_mfma_f32_16x16x32_bf16 v[76:79], v[156:159], v[214:217], v[76:79]
	s_setprio 0
	s_setprio 1
	v_mfma_f32_16x16x32_bf16 v[116:119], v[168:171], v[186:189], v[116:119]
	v_mfma_f32_16x16x32_bf16 v[116:119], v[174:177], v[190:193], v[116:119]
	v_mfma_f32_16x16x32_bf16 v[112:115], v[178:181], v[186:189], v[112:115]
	v_mfma_f32_16x16x32_bf16 v[112:115], v[182:185], v[190:193], v[112:115]
	v_mfma_f32_16x16x32_bf16 v[96:99], v[178:181], v[194:197], v[96:99]
	v_mfma_f32_16x16x32_bf16 v[96:99], v[182:185], v[198:201], v[96:99]
	v_mfma_f32_16x16x32_bf16 v[100:103], v[168:171], v[194:197], v[100:103]
	v_mfma_f32_16x16x32_bf16 v[100:103], v[174:177], v[198:201], v[100:103]
	v_mfma_f32_16x16x32_bf16 v[84:87], v[168:171], v[202:205], v[84:87]
	v_mfma_f32_16x16x32_bf16 v[84:87], v[174:177], v[206:209], v[84:87]
	v_mfma_f32_16x16x32_bf16 v[80:83], v[178:181], v[202:205], v[80:83]
	v_mfma_f32_16x16x32_bf16 v[80:83], v[182:185], v[206:209], v[80:83]
	v_mfma_f32_16x16x32_bf16 v[64:67], v[178:181], v[210:213], v[64:67]
	v_mfma_f32_16x16x32_bf16 v[64:67], v[182:185], v[214:217], v[64:67]
	v_mfma_f32_16x16x32_bf16 v[68:71], v[168:171], v[210:213], v[68:71]
	v_mfma_f32_16x16x32_bf16 v[68:71], v[174:177], v[214:217], v[68:71]
	s_setprio 0
	s_barrier
	s_add_i32 s24, s48, s31
	v_lshl_add_u64 v[218:219], v[218:219], 0, s[16:17]
	s_mov_b32 m0, s24
	ds_read_b128 v[186:189], v151 offset:49152
	ds_read_b128 v[190:193], v151 offset:50176
	ds_read_b128 v[194:197], v151 offset:51200
	ds_read_b128 v[198:201], v151 offset:52224
	ds_read_b128 v[202:205], v151 offset:53248
	ds_read_b128 v[206:209], v151 offset:54272
	ds_read_b128 v[210:213], v151 offset:55296
	ds_read_b128 v[214:217], v151 offset:56320
	global_load_lds_dwordx4 v[218:219], off
	s_add_i32 m0, s24, 0x2000
	s_add_u32 s22, s22, 0x160080
	v_lshl_add_u64 v[218:219], v[220:221], 0, s[16:17]
	s_addc_u32 s23, s23, 0
	s_add_i32 s24, s49, s31
	global_load_lds_dwordx4 v[218:219], off
	v_lshl_add_u64 v[218:219], s[22:23], 0, v[132:133]
	s_mov_b32 m0, s24
	s_nop 0
	global_load_lds_dwordx4 v[218:219], off
	v_lshl_add_u64 v[218:219], s[22:23], 0, v[136:137]
	s_add_i32 m0, s24, 0x2000
	s_nop 0
	global_load_lds_dwordx4 v[218:219], off
	v_lshl_add_u64 v[218:219], v[222:223], 0, s[16:17]
	s_mov_b32 m0, s37
	s_nop 0
	global_load_lds_dwordx4 v[218:219], off
	v_lshl_add_u64 v[218:219], v[224:225], 0, s[16:17]
	s_mov_b32 m0, s38
	s_nop 0
	global_load_lds_dwordx4 v[218:219], off
	s_waitcnt vmcnt(8)
	s_waitcnt lgkmcnt(0)
	s_barrier
	s_setprio 1
	s_waitcnt lgkmcnt(0)
	v_mfma_f32_16x16x32_bf16 v[60:63], v[152:155], v[186:189], v[60:63]
	v_mfma_f32_16x16x32_bf16 v[60:63], v[156:159], v[190:193], v[60:63]
	v_mfma_f32_16x16x32_bf16 v[56:59], v[160:163], v[186:189], v[56:59]
	v_mfma_f32_16x16x32_bf16 v[56:59], v[164:167], v[190:193], v[56:59]
	v_mfma_f32_16x16x32_bf16 v[40:43], v[160:163], v[194:197], v[40:43]
	v_mfma_f32_16x16x32_bf16 v[40:43], v[164:167], v[198:201], v[40:43]
	v_mfma_f32_16x16x32_bf16 v[44:47], v[152:155], v[194:197], v[44:47]
	v_mfma_f32_16x16x32_bf16 v[44:47], v[156:159], v[198:201], v[44:47]
	v_mfma_f32_16x16x32_bf16 v[28:31], v[152:155], v[202:205], v[28:31]
	v_mfma_f32_16x16x32_bf16 v[28:31], v[156:159], v[206:209], v[28:31]
	v_mfma_f32_16x16x32_bf16 v[24:27], v[160:163], v[202:205], v[24:27]
	v_mfma_f32_16x16x32_bf16 v[24:27], v[164:167], v[206:209], v[24:27]
	v_mfma_f32_16x16x32_bf16 v[8:11], v[160:163], v[210:213], v[8:11]
	v_mfma_f32_16x16x32_bf16 v[8:11], v[164:167], v[214:217], v[8:11]
	v_mfma_f32_16x16x32_bf16 v[12:15], v[152:155], v[210:213], v[12:15]
	v_mfma_f32_16x16x32_bf16 v[12:15], v[156:159], v[214:217], v[12:15]
	s_setprio 0
	s_setprio 1
	v_mfma_f32_16x16x32_bf16 v[52:55], v[168:171], v[186:189], v[52:55]
	v_mfma_f32_16x16x32_bf16 v[52:55], v[174:177], v[190:193], v[52:55]
	v_mfma_f32_16x16x32_bf16 v[48:51], v[178:181], v[186:189], v[48:51]
	v_mfma_f32_16x16x32_bf16 v[48:51], v[182:185], v[190:193], v[48:51]
	v_mfma_f32_16x16x32_bf16 v[32:35], v[178:181], v[194:197], v[32:35]
	v_mfma_f32_16x16x32_bf16 v[32:35], v[182:185], v[198:201], v[32:35]
	v_mfma_f32_16x16x32_bf16 v[36:39], v[168:171], v[194:197], v[36:39]
	v_mfma_f32_16x16x32_bf16 v[36:39], v[174:177], v[198:201], v[36:39]
	v_mfma_f32_16x16x32_bf16 v[20:23], v[168:171], v[202:205], v[20:23]
	v_mfma_f32_16x16x32_bf16 v[20:23], v[174:177], v[206:209], v[20:23]
	v_mfma_f32_16x16x32_bf16 v[16:19], v[178:181], v[202:205], v[16:19]
	v_mfma_f32_16x16x32_bf16 v[16:19], v[182:185], v[206:209], v[16:19]
	v_mfma_f32_16x16x32_bf16 v[0:3], v[178:181], v[210:213], v[0:3]
	v_mfma_f32_16x16x32_bf16 v[0:3], v[182:185], v[214:217], v[0:3]
	v_mfma_f32_16x16x32_bf16 v[4:7], v[168:171], v[210:213], v[4:7]
	v_mfma_f32_16x16x32_bf16 v[4:7], v[174:177], v[214:217], v[4:7]
	s_setprio 0
	s_barrier
	s_add_i32 s47, s47, 2
	s_add_u32 s20, s20, 0x100
	s_addc_u32 s21, s21, 0
	s_cmpk_gt_u32 s47, 0x55
	s_cbranch_scc0 .LBB0_849
	s_add_u32 s20, s45, 0xffffff00
	s_addc_u32 s21, s46, -1
	s_and_b64 vcc, exec, s[4:5]
	s_cbranch_vccnz .LBB0_852
	v_mov_b32_e32 v0, 0
	s_mov_b32 s12, s42
	s_mov_b32 s13, s43
	s_mov_b64 s[14:15], s[18:19]
	s_mov_b32 s39, s44
	v_mov_b32_e32 v1, v0
	v_mov_b32_e32 v2, v0
	v_mov_b32_e32 v3, v0
	v_mov_b32_e32 v4, v0
	v_mov_b32_e32 v5, v0
	v_mov_b32_e32 v6, v0
	v_mov_b32_e32 v7, v0
	v_mov_b32_e32 v16, v0
	v_mov_b32_e32 v17, v0
	v_mov_b32_e32 v18, v0
	v_mov_b32_e32 v19, v0
	v_mov_b32_e32 v20, v0
	v_mov_b32_e32 v21, v0
	v_mov_b32_e32 v22, v0
	v_mov_b32_e32 v23, v0
	v_mov_b32_e32 v32, v0
	v_mov_b32_e32 v33, v0
	v_mov_b32_e32 v34, v0
	v_mov_b32_e32 v35, v0
	v_mov_b32_e32 v36, v0
	v_mov_b32_e32 v37, v0
	v_mov_b32_e32 v38, v0
	v_mov_b32_e32 v39, v0
	v_mov_b32_e32 v48, v0
	v_mov_b32_e32 v49, v0
	v_mov_b32_e32 v50, v0
	v_mov_b32_e32 v51, v0
	v_mov_b32_e32 v52, v0
	v_mov_b32_e32 v53, v0
	v_mov_b32_e32 v54, v0
	v_mov_b32_e32 v55, v0
	v_mov_b32_e32 v8, v0
	v_mov_b32_e32 v9, v0
	v_mov_b32_e32 v10, v0
	v_mov_b32_e32 v11, v0
	v_mov_b32_e32 v12, v0
	v_mov_b32_e32 v13, v0
	v_mov_b32_e32 v14, v0
	v_mov_b32_e32 v15, v0
	v_mov_b32_e32 v24, v0
	v_mov_b32_e32 v25, v0
	v_mov_b32_e32 v26, v0
	v_mov_b32_e32 v27, v0
	v_mov_b32_e32 v28, v0
	v_mov_b32_e32 v29, v0
	v_mov_b32_e32 v30, v0
	v_mov_b32_e32 v31, v0
	v_mov_b32_e32 v40, v0
	v_mov_b32_e32 v41, v0
	v_mov_b32_e32 v42, v0
	v_mov_b32_e32 v43, v0
	v_mov_b32_e32 v44, v0
	v_mov_b32_e32 v45, v0
	v_mov_b32_e32 v46, v0
	v_mov_b32_e32 v47, v0
	v_mov_b32_e32 v56, v0
	v_mov_b32_e32 v57, v0
	v_mov_b32_e32 v58, v0
	v_mov_b32_e32 v59, v0
	v_mov_b32_e32 v60, v0
	v_mov_b32_e32 v61, v0
	v_mov_b32_e32 v62, v0
	v_mov_b32_e32 v63, v0
	v_mov_b32_e32 v64, v0
	v_mov_b32_e32 v65, v0
	v_mov_b32_e32 v66, v0
	v_mov_b32_e32 v67, v0
	v_mov_b32_e32 v68, v0
	v_mov_b32_e32 v69, v0
	v_mov_b32_e32 v70, v0
	v_mov_b32_e32 v71, v0
	v_mov_b32_e32 v80, v0
	v_mov_b32_e32 v81, v0
	v_mov_b32_e32 v82, v0
	v_mov_b32_e32 v83, v0
	v_mov_b32_e32 v84, v0
	v_mov_b32_e32 v85, v0
	v_mov_b32_e32 v86, v0
	v_mov_b32_e32 v87, v0
	v_mov_b32_e32 v96, v0
	v_mov_b32_e32 v97, v0
	v_mov_b32_e32 v98, v0
	v_mov_b32_e32 v99, v0
	v_mov_b32_e32 v100, v0
	v_mov_b32_e32 v101, v0
	v_mov_b32_e32 v102, v0
	v_mov_b32_e32 v103, v0
	v_mov_b32_e32 v112, v0
	v_mov_b32_e32 v113, v0
	v_mov_b32_e32 v114, v0
	v_mov_b32_e32 v115, v0
	v_mov_b32_e32 v116, v0
	v_mov_b32_e32 v117, v0
	v_mov_b32_e32 v118, v0
	v_mov_b32_e32 v119, v0
	v_mov_b32_e32 v72, v0
	v_mov_b32_e32 v73, v0
	v_mov_b32_e32 v74, v0
	v_mov_b32_e32 v75, v0
	v_mov_b32_e32 v76, v0
	v_mov_b32_e32 v77, v0
	v_mov_b32_e32 v78, v0
	v_mov_b32_e32 v79, v0
	v_mov_b32_e32 v88, v0
	v_mov_b32_e32 v89, v0
	v_mov_b32_e32 v90, v0
	v_mov_b32_e32 v91, v0
	v_mov_b32_e32 v92, v0
	v_mov_b32_e32 v93, v0
	v_mov_b32_e32 v94, v0
	v_mov_b32_e32 v95, v0
	v_mov_b32_e32 v104, v0
	v_mov_b32_e32 v105, v0
	v_mov_b32_e32 v106, v0
	v_mov_b32_e32 v107, v0
	v_mov_b32_e32 v108, v0
	v_mov_b32_e32 v109, v0
	v_mov_b32_e32 v110, v0
	v_mov_b32_e32 v111, v0
	v_mov_b32_e32 v120, v0
	v_mov_b32_e32 v121, v0
	v_mov_b32_e32 v122, v0
	v_mov_b32_e32 v123, v0
	v_mov_b32_e32 v124, v0
	v_mov_b32_e32 v125, v0
	v_mov_b32_e32 v126, v0
	v_mov_b32_e32 v127, v0
	s_andn2_b64 vcc, exec, s[0:1]
	s_cbranch_vccnz .LBB0_853
	s_branch .LBB0_854
